# barrier spin loops pause longer between polls (s_sleep 3 instead of 1): fewer poll loads contending with the release atomics
# baseline (speedup 1.0000x reference)
.LBB0_11:
	s_sleep 3
	global_load_dword v2, v1, s[6:7] offset:32 sc1
	s_waitcnt vmcnt(0)
	v_and_b32_e32 v2, 0xffff0000, v2
	v_cmp_ne_u32_e32 vcc, v2, v0
	s_or_b64 s[8:9], vcc, s[8:9]
	s_andn2_b64 exec, exec, s[8:9]
	s_cbranch_execnz .LBB0_11

.LBB0_158:
	global_load_dword v15, v16, s[28:29] offset:1024 sc1
	s_waitcnt lgkmcnt(0)
	global_load_dword v0, v16, s[28:29] offset:1280 sc1
	global_load_dword v1, v16, s[28:29] offset:1536 sc1
	global_load_dword v2, v16, s[28:29] offset:1792 sc1
	global_load_dword v3, v16, s[28:29] offset:2048 sc1
	global_load_dword v4, v16, s[28:29] offset:2304 sc1
	global_load_dword v5, v16, s[28:29] offset:2560 sc1
	global_load_dword v6, v16, s[28:29] offset:2816 sc1
	global_load_dword v7, v16, s[28:29] offset:3072 sc1
	global_load_dword v8, v16, s[28:29] offset:3328 sc1
	global_load_dword v9, v16, s[28:29] offset:3584 sc1
	global_load_dword v10, v16, s[28:29] offset:3840 sc1
	global_load_dword v11, v16, s[4:5] sc1
	global_load_dword v12, v16, s[8:9] sc1
	global_load_dword v13, v16, s[14:15] sc1
	global_load_dword v14, v16, s[18:19] sc1
	s_mov_b64 s[82:83], -1
	s_mov_b64 s[84:85], -1
	s_waitcnt vmcnt(14)
	v_add_u32_e32 v17, v0, v15
	s_waitcnt vmcnt(13)
	v_add_u32_e32 v17, v17, v1
	s_waitcnt vmcnt(12)
	v_add_u32_e32 v17, v17, v2
	s_waitcnt vmcnt(11)
	v_add_u32_e32 v17, v17, v3
	s_waitcnt vmcnt(10)
	v_add_u32_e32 v17, v17, v4
	s_waitcnt vmcnt(9)
	v_add_u32_e32 v17, v17, v5
	s_waitcnt vmcnt(8)
	v_add_u32_e32 v17, v17, v6
	s_waitcnt vmcnt(7)
	v_add_u32_e32 v17, v17, v7
	s_waitcnt vmcnt(6)
	v_add_u32_e32 v17, v17, v8
	s_waitcnt vmcnt(5)
	v_add_u32_e32 v17, v17, v9
	s_waitcnt vmcnt(4)
	v_add_u32_e32 v17, v17, v10
	s_waitcnt vmcnt(3)
	v_add_u32_e32 v17, v17, v11
	s_waitcnt vmcnt(2)
	v_add_u32_e32 v17, v17, v12
	s_waitcnt vmcnt(1)
	v_add_u32_e32 v17, v17, v13
	s_waitcnt vmcnt(0)
	v_add_u32_e32 v17, v17, v14
	v_cmp_eq_u32_e32 vcc, s3, v17
	s_cbranch_vccnz .LBB0_157
	s_and_b32 s17, s16, 0xff
	s_cmp_eq_u32 s17, 0
	s_mov_b64 s[86:87], -1
	s_sleep 3
	s_cbranch_scc0 .LBB0_162
	global_load_dword v17, v16, s[28:29] offset:512 sc1
	s_waitcnt vmcnt(0)
	v_cmp_eq_u32_e32 vcc, 0, v17
	s_cbranch_vccnz .LBB0_164
	s_mov_b64 s[86:87], 0

.LBB0_176:
	s_and_b32 s16, s3, 0xff
	s_mov_b64 s[86:87], -1
	s_cmp_lg_u32 s16, 0
	s_mov_b64 s[90:91], -1
	s_sleep 3
	s_cbranch_scc1 .LBB0_179
	global_load_dword v2, v0, s[28:29] offset:512 sc1
	s_waitcnt vmcnt(0)
	v_cmp_eq_u32_e32 vcc, 0, v2
	s_cbranch_vccnz .LBB0_181
	s_mov_b64 s[90:91], 0
	s_mov_b64 s[88:89], -1

.LBB0_193:
	s_and_b32 s16, s3, 0xff
	s_cmp_lg_u32 s16, 0
	s_mov_b64 s[90:91], -1
	s_sleep 3
	s_cbranch_scc1 .LBB0_196
	global_load_dword v1, v0, s[18:19] sc1
	s_waitcnt vmcnt(0)
	v_cmp_eq_u32_e32 vcc, 0, v1
	s_cbranch_vccnz .LBB0_198
	s_mov_b64 s[90:91], 0
	s_mov_b64 s[88:89], -1

.LBB0_237:
	global_load_dword v15, v16, s[28:29] offset:1024 sc1
	s_waitcnt lgkmcnt(0)
	global_load_dword v0, v16, s[28:29] offset:1280 sc1
	global_load_dword v1, v16, s[28:29] offset:1536 sc1
	global_load_dword v2, v16, s[28:29] offset:1792 sc1
	global_load_dword v3, v16, s[28:29] offset:2048 sc1
	global_load_dword v4, v16, s[28:29] offset:2304 sc1
	global_load_dword v5, v16, s[28:29] offset:2560 sc1
	global_load_dword v6, v16, s[28:29] offset:2816 sc1
	global_load_dword v7, v16, s[28:29] offset:3072 sc1
	global_load_dword v8, v16, s[28:29] offset:3328 sc1
	global_load_dword v9, v16, s[28:29] offset:3584 sc1
	global_load_dword v10, v16, s[28:29] offset:3840 sc1
	global_load_dword v11, v16, s[4:5] sc1
	global_load_dword v12, v16, s[6:7] sc1
	global_load_dword v13, v16, s[8:9] sc1
	global_load_dword v14, v16, s[10:11] sc1
	s_mov_b64 s[12:13], -1
	s_mov_b64 s[14:15], -1
	s_waitcnt vmcnt(14)
	v_add_u32_e32 v17, v0, v15
	s_waitcnt vmcnt(13)
	v_add_u32_e32 v17, v17, v1
	s_waitcnt vmcnt(12)
	v_add_u32_e32 v17, v17, v2
	s_waitcnt vmcnt(11)
	v_add_u32_e32 v17, v17, v3
	s_waitcnt vmcnt(10)
	v_add_u32_e32 v17, v17, v4
	s_waitcnt vmcnt(9)
	v_add_u32_e32 v17, v17, v5
	s_waitcnt vmcnt(8)
	v_add_u32_e32 v17, v17, v6
	s_waitcnt vmcnt(7)
	v_add_u32_e32 v17, v17, v7
	s_waitcnt vmcnt(6)
	v_add_u32_e32 v17, v17, v8
	s_waitcnt vmcnt(5)
	v_add_u32_e32 v17, v17, v9
	s_waitcnt vmcnt(4)
	v_add_u32_e32 v17, v17, v10
	s_waitcnt vmcnt(3)
	v_add_u32_e32 v17, v17, v11
	s_waitcnt vmcnt(2)
	v_add_u32_e32 v17, v17, v12
	s_waitcnt vmcnt(1)
	v_add_u32_e32 v17, v17, v13
	s_waitcnt vmcnt(0)
	v_add_u32_e32 v17, v17, v14
	v_cmp_eq_u32_e32 vcc, s3, v17
	s_cbranch_vccnz .LBB0_236
	s_and_b32 s12, s16, 0xff
	s_cmp_eq_u32 s12, 0
	s_mov_b64 s[12:13], -1
	s_mov_b64 s[20:21], -1
	s_sleep 3
	s_cbranch_scc0 .LBB0_241
	global_load_dword v17, v16, s[28:29] offset:512 sc1
	s_waitcnt vmcnt(0)
	v_cmp_eq_u32_e32 vcc, 0, v17
	s_cbranch_vccnz .LBB0_243
	s_mov_b64 s[20:21], 0

.LBB0_255:
	s_and_b32 s16, s3, 0xff
	s_mov_b64 s[20:21], -1
	s_cmp_lg_u32 s16, 0
	s_mov_b64 s[62:63], -1
	s_sleep 3
	s_cbranch_scc1 .LBB0_258
	global_load_dword v2, v0, s[28:29] offset:512 sc1
	s_waitcnt vmcnt(0)
	v_cmp_eq_u32_e32 vcc, 0, v2
	s_cbranch_vccnz .LBB0_260
	s_mov_b64 s[62:63], 0
	s_mov_b64 s[50:51], -1

.LBB0_272:
	s_and_b32 s16, s3, 0xff
	s_cmp_lg_u32 s16, 0
	s_mov_b64 s[62:63], -1
	s_sleep 3
	s_cbranch_scc1 .LBB0_275
	global_load_dword v1, v0, s[10:11] sc1
	s_waitcnt vmcnt(0)
	v_cmp_eq_u32_e32 vcc, 0, v1
	s_cbranch_vccnz .LBB0_277
	s_mov_b64 s[62:63], 0
	s_mov_b64 s[50:51], -1

.LBB0_471:
	s_and_b32 s16, s3, 0xff
	s_mov_b64 s[20:21], -1
	s_cmp_lg_u32 s16, 0
	s_mov_b64 s[74:75], -1
	s_sleep 3
	s_cbranch_scc1 .LBB0_474
	global_load_dword v2, v0, s[28:29] offset:512 sc1
	s_waitcnt vmcnt(0)
	v_cmp_eq_u32_e32 vcc, 0, v2
	s_cbranch_vccnz .LBB0_476
	s_mov_b64 s[74:75], 0
	s_mov_b64 s[68:69], -1

.LBB0_488:
	s_and_b32 s16, s3, 0xff
	s_cmp_lg_u32 s16, 0
	s_mov_b64 s[74:75], -1
	s_sleep 3
	s_cbranch_scc1 .LBB0_491
	global_load_dword v1, v0, s[10:11] sc1
	s_waitcnt vmcnt(0)
	v_cmp_eq_u32_e32 vcc, 0, v1
	s_cbranch_vccnz .LBB0_493
	s_mov_b64 s[74:75], 0
	s_mov_b64 s[68:69], -1

.LBB0_541:
	s_and_b32 s16, s3, 0xff
	s_mov_b64 s[20:21], -1
	s_cmp_lg_u32 s16, 0
	s_mov_b64 s[52:53], -1
	s_sleep 3
	s_cbranch_scc1 .LBB0_544
	global_load_dword v2, v0, s[28:29] offset:512 sc1
	s_waitcnt vmcnt(0)
	v_cmp_eq_u32_e32 vcc, 0, v2
	s_cbranch_vccnz .LBB0_546
	s_mov_b64 s[52:53], 0
	s_mov_b64 s[48:49], -1

.LBB0_558:
	s_and_b32 s16, s3, 0xff
	s_cmp_lg_u32 s16, 0
	s_mov_b64 s[52:53], -1
	s_sleep 3
	s_cbranch_scc1 .LBB0_561
	global_load_dword v1, v0, s[10:11] sc1
	s_waitcnt vmcnt(0)
	v_cmp_eq_u32_e32 vcc, 0, v1
	s_cbranch_vccnz .LBB0_563
	s_mov_b64 s[52:53], 0
	s_mov_b64 s[48:49], -1

.LBB0_772:
	s_and_b32 s16, s3, 0xff
	s_mov_b64 s[20:21], -1
	s_cmp_lg_u32 s16, 0
	s_mov_b64 s[24:25], -1
	s_sleep 3
	s_cbranch_scc1 .LBB0_775
	global_load_dword v2, v0, s[28:29] offset:512 sc1
	s_waitcnt vmcnt(0)
	v_cmp_eq_u32_e32 vcc, 0, v2
	s_cbranch_vccnz .LBB0_777
	s_mov_b64 s[24:25], 0
	s_mov_b64 s[22:23], -1

.LBB0_789:
	s_and_b32 s16, s3, 0xff
	s_cmp_lg_u32 s16, 0
	s_mov_b64 s[24:25], -1
	s_sleep 3
	s_cbranch_scc1 .LBB0_792
	global_load_dword v1, v0, s[10:11] sc1
	s_waitcnt vmcnt(0)
	v_cmp_eq_u32_e32 vcc, 0, v1
	s_cbranch_vccnz .LBB0_794
	s_mov_b64 s[24:25], 0
	s_mov_b64 s[22:23], -1

.LBB0_947:
	global_load_dword v15, v16, s[28:29] offset:1024 sc1
	s_waitcnt lgkmcnt(0)
	global_load_dword v0, v16, s[28:29] offset:1280 sc1
	global_load_dword v1, v16, s[28:29] offset:1536 sc1
	global_load_dword v2, v16, s[28:29] offset:1792 sc1
	global_load_dword v3, v16, s[28:29] offset:2048 sc1
	global_load_dword v4, v16, s[28:29] offset:2304 sc1
	global_load_dword v5, v16, s[28:29] offset:2560 sc1
	global_load_dword v6, v16, s[28:29] offset:2816 sc1
	global_load_dword v7, v16, s[28:29] offset:3072 sc1
	global_load_dword v8, v16, s[28:29] offset:3328 sc1
	global_load_dword v9, v16, s[28:29] offset:3584 sc1
	global_load_dword v10, v16, s[28:29] offset:3840 sc1
	global_load_dword v11, v16, s[4:5] sc1
	global_load_dword v12, v16, s[6:7] sc1
	global_load_dword v13, v16, s[10:11] sc1
	global_load_dword v14, v16, s[12:13] sc1
	s_mov_b64 s[14:15], -1
	s_mov_b64 s[20:21], -1
	s_waitcnt vmcnt(14)
	v_add_u32_e32 v17, v0, v15
	s_waitcnt vmcnt(13)
	v_add_u32_e32 v17, v17, v1
	s_waitcnt vmcnt(12)
	v_add_u32_e32 v17, v17, v2
	s_waitcnt vmcnt(11)
	v_add_u32_e32 v17, v17, v3
	s_waitcnt vmcnt(10)
	v_add_u32_e32 v17, v17, v4
	s_waitcnt vmcnt(9)
	v_add_u32_e32 v17, v17, v5
	s_waitcnt vmcnt(8)
	v_add_u32_e32 v17, v17, v6
	s_waitcnt vmcnt(7)
	v_add_u32_e32 v17, v17, v7
	s_waitcnt vmcnt(6)
	v_add_u32_e32 v17, v17, v8
	s_waitcnt vmcnt(5)
	v_add_u32_e32 v17, v17, v9
	s_waitcnt vmcnt(4)
	v_add_u32_e32 v17, v17, v10
	s_waitcnt vmcnt(3)
	v_add_u32_e32 v17, v17, v11
	s_waitcnt vmcnt(2)
	v_add_u32_e32 v17, v17, v12
	s_waitcnt vmcnt(1)
	v_add_u32_e32 v17, v17, v13
	s_waitcnt vmcnt(0)
	v_add_u32_e32 v17, v17, v14
	v_cmp_eq_u32_e32 vcc, s3, v17
	s_cbranch_vccnz .LBB0_946
	s_and_b32 s14, s16, 0xff
	s_cmp_eq_u32 s14, 0
	s_mov_b64 s[14:15], -1
	s_mov_b64 s[22:23], -1
	s_sleep 3
	s_cbranch_scc0 .LBB0_951
	global_load_dword v17, v16, s[28:29] offset:512 sc1
	s_waitcnt vmcnt(0)
	v_cmp_eq_u32_e32 vcc, 0, v17
	s_cbranch_vccnz .LBB0_953
	s_mov_b64 s[22:23], 0

.LBB0_965:
	s_and_b32 s16, s3, 0xff
	s_mov_b64 s[22:23], -1
	s_cmp_lg_u32 s16, 0
	s_mov_b64 s[40:41], -1
	s_sleep 3
	s_cbranch_scc1 .LBB0_968
	global_load_dword v2, v0, s[28:29] offset:512 sc1
	s_waitcnt vmcnt(0)
	v_cmp_eq_u32_e32 vcc, 0, v2
	s_cbranch_vccnz .LBB0_970
	s_mov_b64 s[40:41], 0
	s_mov_b64 s[24:25], -1

.LBB0_982:
	s_and_b32 s16, s3, 0xff
	s_cmp_lg_u32 s16, 0
	s_mov_b64 s[40:41], -1
	s_sleep 3
	s_cbranch_scc1 .LBB0_985
	global_load_dword v1, v0, s[12:13] sc1
	s_waitcnt vmcnt(0)
	v_cmp_eq_u32_e32 vcc, 0, v1
	s_cbranch_vccnz .LBB0_987
	s_mov_b64 s[40:41], 0
	s_mov_b64 s[24:25], -1

.LBB0_1020:
	s_and_b32 s16, s3, 0xff
	s_mov_b64 s[22:23], -1
	s_cmp_lg_u32 s16, 0
	s_mov_b64 s[36:37], -1
	s_sleep 3
	s_cbranch_scc1 .LBB0_1023
	global_load_dword v2, v0, s[28:29] offset:512 sc1
	s_waitcnt vmcnt(0)
	v_cmp_eq_u32_e32 vcc, 0, v2
	s_cbranch_vccnz .LBB0_1025
	s_mov_b64 s[36:37], 0
	s_mov_b64 s[24:25], -1

.LBB0_1037:
	s_and_b32 s16, s3, 0xff
	s_cmp_lg_u32 s16, 0
	s_mov_b64 s[36:37], -1
	s_sleep 3
	s_cbranch_scc1 .LBB0_1040
	global_load_dword v1, v0, s[12:13] sc1
	s_waitcnt vmcnt(0)
	v_cmp_eq_u32_e32 vcc, 0, v1
	s_cbranch_vccnz .LBB0_1042
	s_mov_b64 s[36:37], 0
	s_mov_b64 s[24:25], -1

.LBB0_1270:
	global_load_dword v15, v16, s[28:29] offset:1024 sc1
	s_waitcnt lgkmcnt(0)
	global_load_dword v0, v16, s[28:29] offset:1280 sc1
	global_load_dword v1, v16, s[28:29] offset:1536 sc1
	global_load_dword v2, v16, s[28:29] offset:1792 sc1
	global_load_dword v3, v16, s[28:29] offset:2048 sc1
	global_load_dword v4, v16, s[28:29] offset:2304 sc1
	global_load_dword v5, v16, s[28:29] offset:2560 sc1
	global_load_dword v6, v16, s[28:29] offset:2816 sc1
	global_load_dword v7, v16, s[28:29] offset:3072 sc1
	global_load_dword v8, v16, s[28:29] offset:3328 sc1
	global_load_dword v9, v16, s[28:29] offset:3584 sc1
	global_load_dword v10, v16, s[28:29] offset:3840 sc1
	global_load_dword v11, v16, s[2:3] sc1
	global_load_dword v12, v16, s[4:5] sc1
	global_load_dword v13, v16, s[6:7] sc1
	global_load_dword v14, v16, s[10:11] sc1
	s_mov_b64 s[12:13], -1
	s_mov_b64 s[14:15], -1
	s_waitcnt vmcnt(14)
	v_add_u32_e32 v17, v0, v15
	s_waitcnt vmcnt(13)
	v_add_u32_e32 v17, v17, v1
	s_waitcnt vmcnt(12)
	v_add_u32_e32 v17, v17, v2
	s_waitcnt vmcnt(11)
	v_add_u32_e32 v17, v17, v3
	s_waitcnt vmcnt(10)
	v_add_u32_e32 v17, v17, v4
	s_waitcnt vmcnt(9)
	v_add_u32_e32 v17, v17, v5
	s_waitcnt vmcnt(8)
	v_add_u32_e32 v17, v17, v6
	s_waitcnt vmcnt(7)
	v_add_u32_e32 v17, v17, v7
	s_waitcnt vmcnt(6)
	v_add_u32_e32 v17, v17, v8
	s_waitcnt vmcnt(5)
	v_add_u32_e32 v17, v17, v9
	s_waitcnt vmcnt(4)
	v_add_u32_e32 v17, v17, v10
	s_waitcnt vmcnt(3)
	v_add_u32_e32 v17, v17, v11
	s_waitcnt vmcnt(2)
	v_add_u32_e32 v17, v17, v12
	s_waitcnt vmcnt(1)
	v_add_u32_e32 v17, v17, v13
	s_waitcnt vmcnt(0)
	v_add_u32_e32 v17, v17, v14
	v_cmp_eq_u32_e32 vcc, s18, v17
	s_cbranch_vccnz .LBB0_1269
	s_and_b32 s12, s19, 0xff
	s_cmp_eq_u32 s12, 0
	s_mov_b64 s[12:13], -1
	s_mov_b64 s[16:17], -1
	s_sleep 3
	s_cbranch_scc0 .LBB0_1274
	global_load_dword v17, v16, s[28:29] offset:512 sc1
	s_waitcnt vmcnt(0)
	v_cmp_eq_u32_e32 vcc, 0, v17
	s_cbranch_vccnz .LBB0_1276
	s_mov_b64 s[16:17], 0

.LBB0_1288:
	s_and_b32 s18, s22, 0xff
	s_mov_b64 s[16:17], -1
	s_cmp_lg_u32 s18, 0
	s_mov_b64 s[20:21], -1
	s_sleep 3
	s_cbranch_scc1 .LBB0_1291
	global_load_dword v2, v0, s[28:29] offset:512 sc1
	s_waitcnt vmcnt(0)
	v_cmp_eq_u32_e32 vcc, 0, v2
	s_cbranch_vccnz .LBB0_1293
	s_mov_b64 s[20:21], 0
	s_mov_b64 s[18:19], -1

.LBB0_1305:
	s_and_b32 s18, s24, 0xff
	s_cmp_lg_u32 s18, 0
	s_mov_b64 s[20:21], -1
	s_sleep 3
	s_cbranch_scc1 .LBB0_1308
	global_load_dword v1, v0, s[10:11] sc1
	s_waitcnt vmcnt(0)
	v_cmp_eq_u32_e32 vcc, 0, v1
	s_cbranch_vccnz .LBB0_1310
	s_mov_b64 s[20:21], 0
	s_mov_b64 s[18:19], -1
